# v083 + P7 SwiGLU epilogue: HG output stores marked non-temporal (nt) so the 2 MB/round of write-once data does not displace GEMM operand lines in L2
# speedup vs baseline: 1.0054x; 1.0054x over previous
.Lp7_epi_cached:
	v_mad_i64_i32 v[160:161], s[42:43], v148, s51, v[144:145]
	v_lshlrev_b64 v[146:147], 1, v[146:147]
	s_mov_b32 s66, 0x2c000
	s_mov_b32 s67, 0
	v_lshl_add_u64 v[160:161], v[160:161], 0, v[146:147]
	v_rsq_f32_e32 v176, v241
	v_pk_mul_f32 v[116:117], v[124:125], v[116:117]
	v_pk_mul_f32 v[118:119], v[126:127], v[118:119]
	v_pk_mul_f32 v[112:113], v[120:121], v[112:113]
	v_pk_mul_f32 v[114:115], v[122:123], v[114:115]
	v_mul_f32_e32 v177, 0xbfb8aa3b, v176
	v_mul_f32_e32 v162, v177, v124
	v_mul_f32_e32 v163, v177, v125
	v_mul_f32_e32 v164, v177, v126
	v_mul_f32_e32 v165, v177, v127
	v_mul_f32_e32 v166, v177, v120
	v_mul_f32_e32 v167, v177, v121
	v_mul_f32_e32 v168, v177, v122
	v_mul_f32_e32 v169, v177, v123
	v_exp_f32_e32 v162, v162
	v_exp_f32_e32 v163, v163
	v_exp_f32_e32 v164, v164
	v_exp_f32_e32 v165, v165
	v_exp_f32_e32 v166, v166
	v_exp_f32_e32 v167, v167
	v_exp_f32_e32 v168, v168
	v_exp_f32_e32 v169, v169
	v_fma_f32 v162, v162, v241, v241
	v_fma_f32 v163, v163, v241, v241
	v_fma_f32 v164, v164, v241, v241
	v_fma_f32 v165, v165, v241, v241
	v_fma_f32 v166, v166, v241, v241
	v_fma_f32 v167, v167, v241, v241
	v_fma_f32 v168, v168, v241, v241
	v_fma_f32 v169, v169, v241, v241
	v_rcp_f32_e32 v162, v162
	v_rcp_f32_e32 v163, v163
	v_rcp_f32_e32 v164, v164
	v_rcp_f32_e32 v165, v165
	v_rcp_f32_e32 v166, v166
	v_rcp_f32_e32 v167, v167
	v_rcp_f32_e32 v168, v168
	v_rcp_f32_e32 v169, v169
	v_pk_mul_f32 v[116:117], v[116:117], v[162:163]
	v_pk_mul_f32 v[118:119], v[118:119], v[164:165]
	v_pk_mul_f32 v[112:113], v[112:113], v[166:167]
	v_pk_mul_f32 v[114:115], v[114:115], v[168:169]
	v_cvt_pk_bf16_f32 v170, v116, v117
	v_cvt_pk_bf16_f32 v171, v118, v119
	v_cvt_pk_bf16_f32 v172, v112, v113
	v_cvt_pk_bf16_f32 v173, v114, v115
	global_store_dwordx4 v[160:161], v[170:173], off nt
	v_lshl_add_u64 v[160:161], v[160:161], 0, s[66:67]
	v_rsq_f32_e32 v176, v242
	v_pk_mul_f32 v[100:101], v[108:109], v[100:101]
	v_pk_mul_f32 v[102:103], v[110:111], v[102:103]
	v_pk_mul_f32 v[96:97], v[104:105], v[96:97]
	v_pk_mul_f32 v[98:99], v[106:107], v[98:99]
	v_mul_f32_e32 v177, 0xbfb8aa3b, v176
	v_mul_f32_e32 v162, v177, v108
	v_mul_f32_e32 v163, v177, v109
	v_mul_f32_e32 v164, v177, v110
	v_mul_f32_e32 v165, v177, v111
	v_mul_f32_e32 v166, v177, v104
	v_mul_f32_e32 v167, v177, v105
	v_mul_f32_e32 v168, v177, v106
	v_mul_f32_e32 v169, v177, v107
	v_exp_f32_e32 v162, v162
	v_exp_f32_e32 v163, v163
	v_exp_f32_e32 v164, v164
	v_exp_f32_e32 v165, v165
	v_exp_f32_e32 v166, v166
	v_exp_f32_e32 v167, v167
	v_exp_f32_e32 v168, v168
	v_exp_f32_e32 v169, v169
	v_fma_f32 v162, v162, v242, v242
	v_fma_f32 v163, v163, v242, v242
	v_fma_f32 v164, v164, v242, v242
	v_fma_f32 v165, v165, v242, v242
	v_fma_f32 v166, v166, v242, v242
	v_fma_f32 v167, v167, v242, v242
	v_fma_f32 v168, v168, v242, v242
	v_fma_f32 v169, v169, v242, v242
	v_rcp_f32_e32 v162, v162
	v_rcp_f32_e32 v163, v163
	v_rcp_f32_e32 v164, v164
	v_rcp_f32_e32 v165, v165
	v_rcp_f32_e32 v166, v166
	v_rcp_f32_e32 v167, v167
	v_rcp_f32_e32 v168, v168
	v_rcp_f32_e32 v169, v169
	v_pk_mul_f32 v[100:101], v[100:101], v[162:163]
	v_pk_mul_f32 v[102:103], v[102:103], v[164:165]
	v_pk_mul_f32 v[96:97], v[96:97], v[166:167]
	v_pk_mul_f32 v[98:99], v[98:99], v[168:169]
	v_cvt_pk_bf16_f32 v170, v100, v101
	v_cvt_pk_bf16_f32 v171, v102, v103
	v_cvt_pk_bf16_f32 v172, v96, v97
	v_cvt_pk_bf16_f32 v173, v98, v99
	global_store_dwordx4 v[160:161], v[170:173], off nt
	v_lshl_add_u64 v[160:161], v[160:161], 0, s[66:67]
	v_rsq_f32_e32 v176, v243
	v_pk_mul_f32 v[84:85], v[92:93], v[84:85]
	v_pk_mul_f32 v[86:87], v[94:95], v[86:87]
	v_pk_mul_f32 v[80:81], v[88:89], v[80:81]
	v_pk_mul_f32 v[82:83], v[90:91], v[82:83]
	v_mul_f32_e32 v177, 0xbfb8aa3b, v176
	v_mul_f32_e32 v162, v177, v92
	v_mul_f32_e32 v163, v177, v93
	v_mul_f32_e32 v164, v177, v94
	v_mul_f32_e32 v165, v177, v95
	v_mul_f32_e32 v166, v177, v88
	v_mul_f32_e32 v167, v177, v89
	v_mul_f32_e32 v168, v177, v90
	v_mul_f32_e32 v169, v177, v91
	v_exp_f32_e32 v162, v162
	v_exp_f32_e32 v163, v163
	v_exp_f32_e32 v164, v164
	v_exp_f32_e32 v165, v165
	v_exp_f32_e32 v166, v166
	v_exp_f32_e32 v167, v167
	v_exp_f32_e32 v168, v168
	v_exp_f32_e32 v169, v169
	v_fma_f32 v162, v162, v243, v243
	v_fma_f32 v163, v163, v243, v243
	v_fma_f32 v164, v164, v243, v243
	v_fma_f32 v165, v165, v243, v243
	v_fma_f32 v166, v166, v243, v243
	v_fma_f32 v167, v167, v243, v243
	v_fma_f32 v168, v168, v243, v243
	v_fma_f32 v169, v169, v243, v243
	v_rcp_f32_e32 v162, v162
	v_rcp_f32_e32 v163, v163
	v_rcp_f32_e32 v164, v164
	v_rcp_f32_e32 v165, v165
	v_rcp_f32_e32 v166, v166
	v_rcp_f32_e32 v167, v167
	v_rcp_f32_e32 v168, v168
	v_rcp_f32_e32 v169, v169
	v_pk_mul_f32 v[84:85], v[84:85], v[162:163]
	v_pk_mul_f32 v[86:87], v[86:87], v[164:165]
	v_pk_mul_f32 v[80:81], v[80:81], v[166:167]
	v_pk_mul_f32 v[82:83], v[82:83], v[168:169]
	v_cvt_pk_bf16_f32 v170, v84, v85
	v_cvt_pk_bf16_f32 v171, v86, v87
	v_cvt_pk_bf16_f32 v172, v80, v81
	v_cvt_pk_bf16_f32 v173, v82, v83
	global_store_dwordx4 v[160:161], v[170:173], off nt
	v_lshl_add_u64 v[160:161], v[160:161], 0, s[66:67]
	v_rsq_f32_e32 v176, v244
	v_pk_mul_f32 v[68:69], v[76:77], v[68:69]
	v_pk_mul_f32 v[70:71], v[78:79], v[70:71]
	v_pk_mul_f32 v[64:65], v[72:73], v[64:65]
	v_pk_mul_f32 v[66:67], v[74:75], v[66:67]
	v_mul_f32_e32 v177, 0xbfb8aa3b, v176
	v_mul_f32_e32 v162, v177, v76
	v_mul_f32_e32 v163, v177, v77
	v_mul_f32_e32 v164, v177, v78
	v_mul_f32_e32 v165, v177, v79
	v_mul_f32_e32 v166, v177, v72
	v_mul_f32_e32 v167, v177, v73
	v_mul_f32_e32 v168, v177, v74
	v_mul_f32_e32 v169, v177, v75
	v_exp_f32_e32 v162, v162
	v_exp_f32_e32 v163, v163
	v_exp_f32_e32 v164, v164
	v_exp_f32_e32 v165, v165
	v_exp_f32_e32 v166, v166
	v_exp_f32_e32 v167, v167
	v_exp_f32_e32 v168, v168
	v_exp_f32_e32 v169, v169
	v_fma_f32 v162, v162, v244, v244
	v_fma_f32 v163, v163, v244, v244
	v_fma_f32 v164, v164, v244, v244
	v_fma_f32 v165, v165, v244, v244
	v_fma_f32 v166, v166, v244, v244
	v_fma_f32 v167, v167, v244, v244
	v_fma_f32 v168, v168, v244, v244
	v_fma_f32 v169, v169, v244, v244
	v_rcp_f32_e32 v162, v162
	v_rcp_f32_e32 v163, v163
	v_rcp_f32_e32 v164, v164
	v_rcp_f32_e32 v165, v165
	v_rcp_f32_e32 v166, v166
	v_rcp_f32_e32 v167, v167
	v_rcp_f32_e32 v168, v168
	v_rcp_f32_e32 v169, v169
	v_pk_mul_f32 v[68:69], v[68:69], v[162:163]
	v_pk_mul_f32 v[70:71], v[70:71], v[164:165]
	v_pk_mul_f32 v[64:65], v[64:65], v[166:167]
	v_pk_mul_f32 v[66:67], v[66:67], v[168:169]
	v_cvt_pk_bf16_f32 v170, v68, v69
	v_cvt_pk_bf16_f32 v171, v70, v71
	v_cvt_pk_bf16_f32 v172, v64, v65
	v_cvt_pk_bf16_f32 v173, v66, v67
	global_store_dwordx4 v[160:161], v[170:173], off nt
	s_mov_b32 s66, 0xdc000
	v_lshl_add_u64 v[160:161], v[160:161], 0, s[66:67]
	v_rsq_f32_e32 v176, v245
	v_pk_mul_f32 v[52:53], v[60:61], v[52:53]
	v_pk_mul_f32 v[54:55], v[62:63], v[54:55]
	v_pk_mul_f32 v[48:49], v[56:57], v[48:49]
	v_pk_mul_f32 v[50:51], v[58:59], v[50:51]
	v_mul_f32_e32 v177, 0xbfb8aa3b, v176
	v_mul_f32_e32 v162, v177, v60
	v_mul_f32_e32 v163, v177, v61
	v_mul_f32_e32 v164, v177, v62
	v_mul_f32_e32 v165, v177, v63
	v_mul_f32_e32 v166, v177, v56
	v_mul_f32_e32 v167, v177, v57
	v_mul_f32_e32 v168, v177, v58
	v_mul_f32_e32 v169, v177, v59
	v_exp_f32_e32 v162, v162
	v_exp_f32_e32 v163, v163
	v_exp_f32_e32 v164, v164
	v_exp_f32_e32 v165, v165
	v_exp_f32_e32 v166, v166
	v_exp_f32_e32 v167, v167
	v_exp_f32_e32 v168, v168
	v_exp_f32_e32 v169, v169
	v_fma_f32 v162, v162, v245, v245
	v_fma_f32 v163, v163, v245, v245
	v_fma_f32 v164, v164, v245, v245
	v_fma_f32 v165, v165, v245, v245
	v_fma_f32 v166, v166, v245, v245
	v_fma_f32 v167, v167, v245, v245
	v_fma_f32 v168, v168, v245, v245
	v_fma_f32 v169, v169, v245, v245
	v_rcp_f32_e32 v162, v162
	v_rcp_f32_e32 v163, v163
	v_rcp_f32_e32 v164, v164
	v_rcp_f32_e32 v165, v165
	v_rcp_f32_e32 v166, v166
	v_rcp_f32_e32 v167, v167
	v_rcp_f32_e32 v168, v168
	v_rcp_f32_e32 v169, v169
	v_pk_mul_f32 v[52:53], v[52:53], v[162:163]
	v_pk_mul_f32 v[54:55], v[54:55], v[164:165]
	v_pk_mul_f32 v[48:49], v[48:49], v[166:167]
	v_pk_mul_f32 v[50:51], v[50:51], v[168:169]
	v_cvt_pk_bf16_f32 v170, v52, v53
	v_cvt_pk_bf16_f32 v171, v54, v55
	v_cvt_pk_bf16_f32 v172, v48, v49
	v_cvt_pk_bf16_f32 v173, v50, v51
	global_store_dwordx4 v[160:161], v[170:173], off nt
	s_mov_b32 s66, 0x2c000
	v_lshl_add_u64 v[160:161], v[160:161], 0, s[66:67]
	v_rsq_f32_e32 v176, v246
	v_pk_mul_f32 v[36:37], v[44:45], v[36:37]
	v_pk_mul_f32 v[38:39], v[46:47], v[38:39]
	v_pk_mul_f32 v[32:33], v[40:41], v[32:33]
	v_pk_mul_f32 v[34:35], v[42:43], v[34:35]
	v_mul_f32_e32 v177, 0xbfb8aa3b, v176
	v_mul_f32_e32 v162, v177, v44
	v_mul_f32_e32 v163, v177, v45
	v_mul_f32_e32 v164, v177, v46
	v_mul_f32_e32 v165, v177, v47
	v_mul_f32_e32 v166, v177, v40
	v_mul_f32_e32 v167, v177, v41
	v_mul_f32_e32 v168, v177, v42
	v_mul_f32_e32 v169, v177, v43
	v_exp_f32_e32 v162, v162
	v_exp_f32_e32 v163, v163
	v_exp_f32_e32 v164, v164
	v_exp_f32_e32 v165, v165
	v_exp_f32_e32 v166, v166
	v_exp_f32_e32 v167, v167
	v_exp_f32_e32 v168, v168
	v_exp_f32_e32 v169, v169
	v_fma_f32 v162, v162, v246, v246
	v_fma_f32 v163, v163, v246, v246
	v_fma_f32 v164, v164, v246, v246
	v_fma_f32 v165, v165, v246, v246
	v_fma_f32 v166, v166, v246, v246
	v_fma_f32 v167, v167, v246, v246
	v_fma_f32 v168, v168, v246, v246
	v_fma_f32 v169, v169, v246, v246
	v_rcp_f32_e32 v162, v162
	v_rcp_f32_e32 v163, v163
	v_rcp_f32_e32 v164, v164
	v_rcp_f32_e32 v165, v165
	v_rcp_f32_e32 v166, v166
	v_rcp_f32_e32 v167, v167
	v_rcp_f32_e32 v168, v168
	v_rcp_f32_e32 v169, v169
	v_pk_mul_f32 v[36:37], v[36:37], v[162:163]
	v_pk_mul_f32 v[38:39], v[38:39], v[164:165]
	v_pk_mul_f32 v[32:33], v[32:33], v[166:167]
	v_pk_mul_f32 v[34:35], v[34:35], v[168:169]
	v_cvt_pk_bf16_f32 v170, v36, v37
	v_cvt_pk_bf16_f32 v171, v38, v39
	v_cvt_pk_bf16_f32 v172, v32, v33
	v_cvt_pk_bf16_f32 v173, v34, v35
	global_store_dwordx4 v[160:161], v[170:173], off nt
	v_lshl_add_u64 v[160:161], v[160:161], 0, s[66:67]
	v_rsq_f32_e32 v176, v247
	v_pk_mul_f32 v[20:21], v[28:29], v[20:21]
	v_pk_mul_f32 v[22:23], v[30:31], v[22:23]
	v_pk_mul_f32 v[16:17], v[24:25], v[16:17]
	v_pk_mul_f32 v[18:19], v[26:27], v[18:19]
	v_mul_f32_e32 v177, 0xbfb8aa3b, v176
	v_mul_f32_e32 v162, v177, v28
	v_mul_f32_e32 v163, v177, v29
	v_mul_f32_e32 v164, v177, v30
	v_mul_f32_e32 v165, v177, v31
	v_mul_f32_e32 v166, v177, v24
	v_mul_f32_e32 v167, v177, v25
	v_mul_f32_e32 v168, v177, v26
	v_mul_f32_e32 v169, v177, v27
	v_exp_f32_e32 v162, v162
	v_exp_f32_e32 v163, v163
	v_exp_f32_e32 v164, v164
	v_exp_f32_e32 v165, v165
	v_exp_f32_e32 v166, v166
	v_exp_f32_e32 v167, v167
	v_exp_f32_e32 v168, v168
	v_exp_f32_e32 v169, v169
	v_fma_f32 v162, v162, v247, v247
	v_fma_f32 v163, v163, v247, v247
	v_fma_f32 v164, v164, v247, v247
	v_fma_f32 v165, v165, v247, v247
	v_fma_f32 v166, v166, v247, v247
	v_fma_f32 v167, v167, v247, v247
	v_fma_f32 v168, v168, v247, v247
	v_fma_f32 v169, v169, v247, v247
	v_rcp_f32_e32 v162, v162
	v_rcp_f32_e32 v163, v163
	v_rcp_f32_e32 v164, v164
	v_rcp_f32_e32 v165, v165
	v_rcp_f32_e32 v166, v166
	v_rcp_f32_e32 v167, v167
	v_rcp_f32_e32 v168, v168
	v_rcp_f32_e32 v169, v169
	v_pk_mul_f32 v[20:21], v[20:21], v[162:163]
	v_pk_mul_f32 v[22:23], v[22:23], v[164:165]
	v_pk_mul_f32 v[16:17], v[16:17], v[166:167]
	v_pk_mul_f32 v[18:19], v[18:19], v[168:169]
	v_cvt_pk_bf16_f32 v170, v20, v21
	v_cvt_pk_bf16_f32 v171, v22, v23
	v_cvt_pk_bf16_f32 v172, v16, v17
	v_cvt_pk_bf16_f32 v173, v18, v19
	global_store_dwordx4 v[160:161], v[170:173], off nt
	v_lshl_add_u64 v[160:161], v[160:161], 0, s[66:67]
	v_rsq_f32_e32 v176, v248
	v_pk_mul_f32 v[4:5], v[12:13], v[4:5]
	v_pk_mul_f32 v[6:7], v[14:15], v[6:7]
	v_pk_mul_f32 v[0:1], v[8:9], v[0:1]
	v_pk_mul_f32 v[2:3], v[10:11], v[2:3]
	v_mul_f32_e32 v177, 0xbfb8aa3b, v176
	v_mul_f32_e32 v162, v177, v12
	v_mul_f32_e32 v163, v177, v13
	v_mul_f32_e32 v164, v177, v14
	v_mul_f32_e32 v165, v177, v15
	v_mul_f32_e32 v166, v177, v8
	v_mul_f32_e32 v167, v177, v9
	v_mul_f32_e32 v168, v177, v10
	v_mul_f32_e32 v169, v177, v11
	v_exp_f32_e32 v162, v162
	v_exp_f32_e32 v163, v163
	v_exp_f32_e32 v164, v164
	v_exp_f32_e32 v165, v165
	v_exp_f32_e32 v166, v166
	v_exp_f32_e32 v167, v167
	v_exp_f32_e32 v168, v168
	v_exp_f32_e32 v169, v169
	v_fma_f32 v162, v162, v248, v248
	v_fma_f32 v163, v163, v248, v248
	v_fma_f32 v164, v164, v248, v248
	v_fma_f32 v165, v165, v248, v248
	v_fma_f32 v166, v166, v248, v248
	v_fma_f32 v167, v167, v248, v248
	v_fma_f32 v168, v168, v248, v248
	v_fma_f32 v169, v169, v248, v248
	v_rcp_f32_e32 v162, v162
	v_rcp_f32_e32 v163, v163
	v_rcp_f32_e32 v164, v164
	v_rcp_f32_e32 v165, v165
	v_rcp_f32_e32 v166, v166
	v_rcp_f32_e32 v167, v167
	v_rcp_f32_e32 v168, v168
	v_rcp_f32_e32 v169, v169
	v_pk_mul_f32 v[4:5], v[4:5], v[162:163]
	v_pk_mul_f32 v[6:7], v[6:7], v[164:165]
	v_pk_mul_f32 v[0:1], v[0:1], v[166:167]
	v_pk_mul_f32 v[2:3], v[2:3], v[168:169]
	v_cvt_pk_bf16_f32 v170, v4, v5
	v_cvt_pk_bf16_f32 v171, v6, v7
	v_cvt_pk_bf16_f32 v172, v0, v1
	v_cvt_pk_bf16_f32 v173, v2, v3
	global_store_dwordx4 v[160:161], v[170:173], off nt
	s_cbranch_vccnz .LBB0_789
	s_branch .LBB0_788
